# strategy 7 (wider moves): per-pass zero-init of the 16 softmax-shift accumulator registers in differential attention done with 8 v_mov_b64; on top of the combined version
# baseline (speedup 1.0000x reference)
; #define A_GLOAD(KR, VR, CR, JT) { const int s1_ = (JT) * 64; KR = *(const u32x4*)(kp + (size_t)s1_ * ldk); \
;     _Pragma("unroll") for (int i_ = 0; i_ < DVT / 2; ++i_) VR[i_] = *(const u32x4*)(vp + (size_t)(64 * i_) * SEQ + s1_); \
;     if (FOX) { if (tid < 16) { f32x4 t_ = *(const f32x4*)(cbase + s1_ + tid * 4); CR[0] = -t_[0]; CR[1] = -t_[1]; CR[2] = -t_[2]; CR[3] = -t_[3]; } } }
; template <int DVT, bool FOX> ...
;     ...
;   for (int ks = 0; ks < 4; ++ks) qf[ks] = *(const bf16x8*)(qrow + ks * 16 + hh * 8);
; #pragma unroll
;   for (int d = 0; d < DVT; ++d)
; #pragma unroll
;     for (int i = 0; i < 16; ++i) o[d][i] = 0.f;
;   float m = 0.f, l = 0.f;
;   u32x4 kr0, kr1, vr0[DVT / 2], vr1[DVT / 2]; f32x4 cr0 = {0.f, 0.f, 0.f, 0.f}, cr1 = {0.f, 0.f, 0.f, 0.f};
;   const bf16_t* kp = kbase + (size_t)lrow * ldk + lch * 8;
;   const bf16_t* vp = vtbase + (size_t)lrow * SEQ + lch * 8;
;     ...
;   int j = j_hi;
;   A_GLOAD(kr0, vr0, cr0, j);
;   if (j >= 1) A_GLOAD(kr1, vr1, cr1, j - 1);
.LBB0_636:
	s_and_b64 s[2:3], s[12:13], exec
	v_readlane_b32 s2, v254, 3
	v_readlane_b32 s3, v254, 4
	s_cselect_b32 s2, s3, s2
	s_lshl_b32 s3, s2, 8
	s_add_i32 s2, s3, s24
	v_add_u32_e32 v160, s2, v179
	v_ashrrev_i32_e32 v161, 31, v160
	v_mov_b32_e32 v5, v192
	v_lshlrev_b64 v[2:3], 10, v[160:161]
	v_lshl_add_u64 v[162:163], s[6:7], 0, v[2:3]
	v_bfe_u32 v4, v5, 5, 1
	v_ashrrev_i32_e32 v2, 3, v5
	v_lshlrev_b32_e32 v0, 4, v4
	v_lshl_add_u64 v[6:7], v[162:163], 0, v[0:1]
	v_ashrrev_i32_e32 v3, 31, v2
	global_load_dwordx4 v[112:115], v[6:7], off
	global_load_dwordx4 v[116:119], v[6:7], off offset:32
	global_load_dwordx4 v[120:123], v[6:7], off offset:64
	global_load_dwordx4 v[124:127], v[6:7], off offset:96
	v_and_b32_e32 v0, 7, v5
	v_lshlrev_b64 v[6:7], 10, v[2:3]
	v_lshl_add_u64 v[6:7], s[8:9], 0, v[6:7]
	v_lshlrev_b32_e32 v0, 4, v0
	v_lshl_add_u64 v[164:165], v[6:7], 0, v[0:1]
	v_lshlrev_b64 v[6:7], 15, v[2:3]
	s_or_b32 s4, s3, 0xc0
	v_lshl_add_u64 v[6:7], s[10:11], 0, v[6:7]
	s_ashr_i32 s5, s4, 31
	v_lshl_add_u64 v[166:167], v[6:7], 0, v[0:1]
	v_subrev_u32_e32 v217, s8, v164
	v_subrev_u32_e32 v222, s10, v166
	v_add_u32_e32 v227, 0x200000, v222
	s_lshl_b64 s[16:17], s[4:5], 10
	v_lshl_add_u64 v[6:7], v[164:165], 0, s[16:17]
	v_lshl_add_u64 v[8:9], s[4:5], 1, v[166:167]
	global_load_dwordx4 v[128:131], v[6:7], off
	global_load_dwordx4 v[132:135], v[8:9], off
	v_add_co_u32_e32 v6, vcc, 0x200000, v8
	s_addk_i32 s3, 0x100
	s_nop 0
	v_addc_co_u32_e32 v7, vcc, 0, v9, vcc
	global_load_dwordx4 v[136:139], v[6:7], off
	s_ashr_i32 s3, s3, 6
	s_cmp_gt_i32 s3, 1
	v_mov_b32_e32 v168, 0
	v_mov_b64_e32 v[228:229], 0
	v_mov_b64_e32 v[230:231], 0
	v_mov_b64_e32 v[232:233], 0
	v_mov_b64_e32 v[234:235], 0
	v_mov_b64_e32 v[236:237], 0
	v_mov_b64_e32 v[238:239], 0
	v_mov_b64_e32 v[240:241], 0
	v_mov_b64_e32 v[242:243], 0
	s_cselect_b64 s[18:19], -1, 0
	s_cmp_lt_i32 s3, 2
	v_mov_b32_e32 v144, 0
	v_mov_b32_e32 v145, 0
	v_mov_b32_e32 v146, 0
	v_mov_b32_e32 v147, 0
	v_mov_b32_e32 v148, 0
	v_mov_b32_e32 v149, 0
	v_mov_b32_e32 v150, 0
	v_mov_b32_e32 v151, 0
	s_cbranch_scc1 .LBB0_638
	s_sub_i32 s96, s4, 64
	s_lshl_b64 s[14:15], s[96:97], 10
	v_lshl_add_u64 v[6:7], v[164:165], 0, s[14:15]
	v_lshl_add_u64 v[8:9], s[96:97], 1, v[166:167]
	global_load_dwordx4 v[140:143], v[6:7], off
	global_load_dwordx4 v[144:147], v[8:9], off
	v_add_co_u32_e32 v6, vcc, 0x200000, v8
	s_nop 1
	v_addc_co_u32_e32 v7, vcc, 0, v9, vcc
	global_load_dwordx4 v[148:151], v[6:7], off

; DI unsigned pk2(float lo, float hi) { f32x2 v = {lo, hi}; bf16x2v b = __builtin_convertvector(v, bf16x2v); return __builtin_bit_cast(unsigned, b); }
; #define A_GLOAD(KR, VR, CR, JT) { const int s1_ = (JT) * 64; KR = *(const u32x4*)(kp + (size_t)s1_ * ldk); \
;     _Pragma("unroll") for (int i_ = 0; i_ < DVT / 2; ++i_) VR[i_] = *(const u32x4*)(vp + (size_t)(64 * i_) * SEQ + s1_); \
;     if (FOX) { if (tid < 16) { f32x4 t_ = *(const f32x4*)(cbase + s1_ + tid * 4); CR[0] = -t_[0]; CR[1] = -t_[1]; CR[2] = -t_[2]; CR[3] = -t_[3]; } } }
; template <int DVT, bool FOX> ...
;     ...
;   for (int ks = 0; ks < 4; ++ks) qf[ks] = *(const bf16x8*)(qrow + ks * 16 + hh * 8);
; #pragma unroll
;   for (int d = 0; d < DVT; ++d)
; #pragma unroll
;     for (int i = 0; i < 16; ++i) o[d][i] = 0.f;
;   float m = 0.f, l = 0.f;
;   u32x4 kr0, kr1, vr0[DVT / 2], vr1[DVT / 2]; f32x4 cr0 = {0.f, 0.f, 0.f, 0.f}, cr1 = {0.f, 0.f, 0.f, 0.f};
;   const bf16_t* kp = kbase + (size_t)lrow * ldk + lch * 8;
;   const bf16_t* vp = vtbase + (size_t)lrow * SEQ + lch * 8;
;     ...
;   int j = j_hi;
;   A_GLOAD(kr0, vr0, cr0, j);
;   if (j >= 1) A_GLOAD(kr1, vr1, cr1, j - 1);
; DI void diff_phase(const Params& p, const int j_even, char* lds) {
;     ...
;       const float i1 = 1.f / l1;
;       unsigned* o1s = (unsigned*)(lds + DIFF_STASH_OFF) + tid;
; #pragma unroll
;       for (int d = 0; d < 4; ++d)
; #pragma unroll
;         for (int i = 0; i < 8; ++i) o1s[(d * 8 + i) * 512] = pk2(o1[d][2 * i] * i1, o1[d][2 * i + 1] * i1);
;       attn_pass<4, false>(bq + (size_t)(b * SEQ + tq) * 512 + h * 128 + 64, bk + (size_t)(b * SEQ) * 512 + h * 128 + 64, 512,
;                           bvT + (size_t)(bh * 128) * SEQ, nullptr, nkv - 1, my_last, 0, tq, 0.f, o2, l2, lds);
.LBB0_653:
.LBB0_654:
	v_mov_b32_e32 v2, v0
	s_nop 1
	v_permlane32_swap_b32_e32 v0, v2
	v_add_f32_e32 v0, v0, v2
	v_div_scale_f32 v2, s[2:3], v0, v0, 1.0
	v_rcp_f32_e32 v3, v2
	s_barrier
	v_fma_f32 v4, -v2, v3, 1.0
	v_fmac_f32_e32 v3, v4, v3
	v_div_scale_f32 v4, vcc, 1.0, v0, 1.0
	v_mul_f32_e32 v5, v4, v3
	v_fma_f32 v6, -v2, v5, v4
	v_fmac_f32_e32 v5, v6, v3
	v_fma_f32 v2, -v2, v5, v4
	v_div_fmas_f32 v2, v2, v3, v5
	v_div_fixup_f32 v0, v2, v0, 1.0
	v_pk_mul_f32 v[2:3], v[64:65], v[0:1] op_sel_hi:[1,0]
	v_mov_b32_e32 v5, v192
	v_cvt_pk_bf16_f32 v4, v2, v3
	v_pk_mul_f32 v[2:3], v[66:67], v[0:1] op_sel_hi:[1,0]
	v_mov_b32_e32 v166, 0
	v_mov_b64_e32 v[228:229], 0
	v_mov_b64_e32 v[230:231], 0
	v_mov_b64_e32 v[232:233], 0
	v_mov_b64_e32 v[234:235], 0
	v_mov_b64_e32 v[236:237], 0
	v_mov_b64_e32 v[238:239], 0
	v_mov_b64_e32 v[240:241], 0
	v_mov_b64_e32 v[242:243], 0
	v_cvt_pk_bf16_f32 v2, v2, v3
	ds_write2st64_b32 v180, v4, v2 offset0:218 offset1:226
	v_pk_mul_f32 v[2:3], v[68:69], v[0:1] op_sel_hi:[1,0]
	s_waitcnt vmcnt(1)
	v_mov_b32_e32 v144, 0
	v_cvt_pk_bf16_f32 v4, v2, v3
	v_pk_mul_f32 v[2:3], v[70:71], v[0:1] op_sel_hi:[1,0]
	v_mov_b32_e32 v145, 0
	v_cvt_pk_bf16_f32 v2, v2, v3
	ds_write2st64_b32 v180, v4, v2 offset0:234 offset1:242
	v_pk_mul_f32 v[2:3], v[72:73], v[0:1] op_sel_hi:[1,0]
	v_mov_b32_e32 v146, 0
	v_cvt_pk_bf16_f32 v2, v2, v3
	ds_write_b32 v180, v2 offset:64000
	v_pk_mul_f32 v[2:3], v[74:75], v[0:1] op_sel_hi:[1,0]
	v_mov_b32_e32 v147, 0
	v_cvt_pk_bf16_f32 v4, v2, v3
	v_pk_mul_f32 v[2:3], v[76:77], v[0:1] op_sel_hi:[1,0]
	s_waitcnt vmcnt(0)
	v_mov_b32_e32 v148, 0
	v_cvt_pk_bf16_f32 v2, v2, v3
	ds_write2st64_b32 v181, v4, v2 offset0:40 offset1:48
	v_pk_mul_f32 v[2:3], v[78:79], v[0:1] op_sel_hi:[1,0]
	v_mov_b32_e32 v149, 0
	v_cvt_pk_bf16_f32 v4, v2, v3
	v_pk_mul_f32 v[2:3], v[48:49], v[0:1] op_sel_hi:[1,0]
	v_mov_b32_e32 v150, 0
	v_cvt_pk_bf16_f32 v2, v2, v3
	ds_write2st64_b32 v181, v4, v2 offset0:56 offset1:64
	v_pk_mul_f32 v[2:3], v[50:51], v[0:1] op_sel_hi:[1,0]
	v_mov_b32_e32 v151, 0
	v_cvt_pk_bf16_f32 v4, v2, v3
	v_pk_mul_f32 v[2:3], v[52:53], v[0:1] op_sel_hi:[1,0]
	s_nop 0
	v_cvt_pk_bf16_f32 v2, v2, v3
	ds_write2st64_b32 v181, v4, v2 offset0:72 offset1:80
	v_pk_mul_f32 v[2:3], v[54:55], v[0:1] op_sel_hi:[1,0]
	s_nop 0
	v_cvt_pk_bf16_f32 v4, v2, v3
	v_pk_mul_f32 v[2:3], v[56:57], v[0:1] op_sel_hi:[1,0]
	s_nop 0
	v_cvt_pk_bf16_f32 v2, v2, v3
	ds_write2st64_b32 v181, v4, v2 offset0:88 offset1:96
	v_pk_mul_f32 v[2:3], v[58:59], v[0:1] op_sel_hi:[1,0]
	s_nop 0
	v_cvt_pk_bf16_f32 v4, v2, v3
	v_pk_mul_f32 v[2:3], v[60:61], v[0:1] op_sel_hi:[1,0]
	s_nop 0
	v_cvt_pk_bf16_f32 v2, v2, v3
	ds_write2st64_b32 v181, v4, v2 offset0:104 offset1:112
	v_pk_mul_f32 v[2:3], v[62:63], v[0:1] op_sel_hi:[1,0]
	s_nop 0
	v_cvt_pk_bf16_f32 v4, v2, v3
	v_pk_mul_f32 v[2:3], v[32:33], v[0:1] op_sel_hi:[1,0]
	s_nop 0
	v_cvt_pk_bf16_f32 v2, v2, v3
	ds_write2st64_b32 v181, v4, v2 offset0:120 offset1:128
	v_pk_mul_f32 v[2:3], v[34:35], v[0:1] op_sel_hi:[1,0]
	s_nop 0
	v_cvt_pk_bf16_f32 v4, v2, v3
	v_pk_mul_f32 v[2:3], v[36:37], v[0:1] op_sel_hi:[1,0]
	s_nop 0
	v_cvt_pk_bf16_f32 v2, v2, v3
	ds_write2st64_b32 v181, v4, v2 offset0:136 offset1:144
	v_pk_mul_f32 v[2:3], v[38:39], v[0:1] op_sel_hi:[1,0]
	s_nop 0
	v_cvt_pk_bf16_f32 v4, v2, v3
	v_pk_mul_f32 v[2:3], v[40:41], v[0:1] op_sel_hi:[1,0]
	s_nop 0
	v_cvt_pk_bf16_f32 v2, v2, v3
	ds_write2st64_b32 v181, v4, v2 offset0:152 offset1:160
	v_pk_mul_f32 v[2:3], v[42:43], v[0:1] op_sel_hi:[1,0]
	s_nop 0
	v_cvt_pk_bf16_f32 v4, v2, v3
	v_pk_mul_f32 v[2:3], v[44:45], v[0:1] op_sel_hi:[1,0]
	s_nop 0
	v_cvt_pk_bf16_f32 v2, v2, v3
	ds_write2st64_b32 v181, v4, v2 offset0:168 offset1:176
	v_pk_mul_f32 v[2:3], v[46:47], v[0:1] op_sel_hi:[1,0]
	s_nop 0
	v_cvt_pk_bf16_f32 v4, v2, v3
	v_pk_mul_f32 v[2:3], v[16:17], v[0:1] op_sel_hi:[1,0]
	s_nop 0
	v_cvt_pk_bf16_f32 v2, v2, v3
	ds_write2st64_b32 v181, v4, v2 offset0:184 offset1:192
	v_pk_mul_f32 v[2:3], v[18:19], v[0:1] op_sel_hi:[1,0]
	s_nop 0
	v_cvt_pk_bf16_f32 v4, v2, v3
	v_pk_mul_f32 v[2:3], v[20:21], v[0:1] op_sel_hi:[1,0]
	s_nop 0
	v_cvt_pk_bf16_f32 v2, v2, v3
	ds_write2st64_b32 v181, v4, v2 offset0:200 offset1:208
	v_pk_mul_f32 v[2:3], v[22:23], v[0:1] op_sel_hi:[1,0]
	s_nop 0
	v_cvt_pk_bf16_f32 v4, v2, v3
	v_pk_mul_f32 v[2:3], v[24:25], v[0:1] op_sel_hi:[1,0]
	s_nop 0
	v_cvt_pk_bf16_f32 v2, v2, v3
	ds_write2st64_b32 v181, v4, v2 offset0:216 offset1:224
	v_pk_mul_f32 v[2:3], v[26:27], v[0:1] op_sel_hi:[1,0]
	s_nop 0
	v_cvt_pk_bf16_f32 v4, v2, v3
	v_pk_mul_f32 v[2:3], v[28:29], v[0:1] op_sel_hi:[1,0]
	s_nop 0
	v_cvt_pk_bf16_f32 v2, v2, v3
	ds_write2st64_b32 v181, v4, v2 offset0:232 offset1:240
	v_pk_mul_f32 v[2:3], v[30:31], v[0:1] op_sel_hi:[1,0]
	s_nop 0
	v_cvt_pk_bf16_f32 v0, v2, v3
	ds_write_b32 v181, v0 offset:63488
	s_nop 0
	v_bfe_u32 v4, v5, 5, 1
	v_ashrrev_i32_e32 v2, 3, v5
	v_lshlrev_b32_e32 v0, 4, v4
	v_lshl_add_u64 v[6:7], v[162:163], 0, v[0:1]
	v_ashrrev_i32_e32 v3, 31, v2
	global_load_dwordx4 v[112:115], v[6:7], off offset:128
	global_load_dwordx4 v[116:119], v[6:7], off offset:160
	global_load_dwordx4 v[120:123], v[6:7], off offset:192
	global_load_dwordx4 v[124:127], v[6:7], off offset:224
	v_and_b32_e32 v0, 7, v5
	v_lshlrev_b64 v[6:7], 10, v[2:3]
	v_lshl_add_u64 v[6:7], s[8:9], 0, v[6:7]
	v_lshlrev_b32_e32 v0, 4, v0
	v_lshl_add_u64 v[162:163], v[6:7], 0, v[0:1]
	v_lshlrev_b64 v[6:7], 15, v[2:3]
	v_lshl_add_u64 v[6:7], s[10:11], 0, v[6:7]
	v_lshl_add_u64 v[164:165], v[6:7], 0, v[0:1]
	v_subrev_u32_e32 v217, s8, v162
	v_subrev_u32_e32 v222, s10, v164
	v_add_u32_e32 v227, 0x200000, v222
	v_lshl_add_u64 v[6:7], v[162:163], 0, s[16:17]
	v_lshl_add_u64 v[8:9], s[4:5], 1, v[164:165]
	global_load_dwordx4 v[128:131], v[6:7], off offset:128
	global_load_dwordx4 v[132:135], v[8:9], off
	v_add_co_u32_e32 v6, vcc, 0x200000, v8
	s_nop 1
	v_addc_co_u32_e32 v7, vcc, 0, v9, vcc
	global_load_dwordx4 v[136:139], v[6:7], off
	s_andn2_b64 vcc, exec, s[18:19]
	s_cbranch_vccnz .LBB0_656
	s_sub_i32 s96, s4, 64
	s_lshl_b64 s[2:3], s[96:97], 10
	v_lshl_add_u64 v[6:7], v[162:163], 0, s[2:3]
	v_lshl_add_u64 v[8:9], s[96:97], 1, v[164:165]
	global_load_dwordx4 v[140:143], v[6:7], off offset:128
	global_load_dwordx4 v[144:147], v[8:9], off
	v_add_co_u32_e32 v6, vcc, 0x200000, v8
	s_nop 1
	v_addc_co_u32_e32 v7, vcc, 0, v9, vcc
	global_load_dwordx4 v[148:151], v[6:7], off
